# prologue X to bf16 XN loop unrolled x8 (eight loads in flight, one wait per trip) on top of best (WGM4+GQA remap+reversed residual row order+straight-line relu2/bf16 epilogues)
# baseline (speedup 1.0000x reference)
; __device__ __forceinline__ unsigned cvt_pk_bf16(float lo, float hi) { unsigned r; asm volatile("v_cvt_pk_bf16_f32 %0, %1, %2" : "=v"(r) : "v"(lo), "v"(hi)); return r; }
; __global__ void __launch_bounds__(NTHREADS, 2) fwd_kernel(Args args) {
;     ...
;                 const f32x4* xp = (const f32x4*)args.in[0]; const f32x4* xs = (const f32x4*)args.in[1];
;                 const int NP4 = MPROMPT * DM / 4, NT4 = MTOT * DM / 4;
;                 for (int i = gt; i < NT4; i += NGT) { const f32x4 v = i < NP4 ? xp[i] : xs[i - NP4]; u32x2 w; w.x = cvt_pk_bf16(v[0], v[1]); w.y = cvt_pk_bf16(v[2], v[3]); ((u32x2*)XN)[i] = w; }
.LBB0_754:
	s_or_b64 exec, exec, s[0:1]
	s_mov_b32 s0, 0xc00000
	v_cmp_gt_i32_e32 vcc, s0, v4
	s_and_saveexec_b64 s[0:1], vcc
	v_readlane_b32 s12, v254, 57
	v_readlane_b32 s13, v254, 58
	v_readlane_b32 s14, v254, 59
	v_readlane_b32 s15, v254, 60
	v_readlane_b32 s16, v254, 61
	v_readlane_b32 s17, v254, 62
	v_readlane_b32 s18, v254, 63
	v_readlane_b32 s19, v255, 0
	v_readlane_b32 s20, v255, 1
	v_readlane_b32 s21, v255, 2
	v_readlane_b32 s22, v255, 3
	v_readlane_b32 s23, v255, 4
	v_readlane_b32 s24, v255, 5
	v_readlane_b32 s25, v255, 6
	v_readlane_b32 s26, v255, 7
	v_readlane_b32 s27, v255, 8
	s_cbranch_execz .LBB0_757
	v_readlane_b32 s5, v254, 45
	s_add_u32 s2, s5, s2
	v_readlane_b32 s5, v254, 46
	s_addc_u32 s3, s5, s3
	s_ashr_i32 s5, s4, 31
	v_lshl_add_u64 v[2:3], v[4:5], 3, s[2:3]
	s_lshl_b64 s[2:3], s[4:5], 3
	v_lshl_add_u64 v[6:7], v[4:5], 4, s[12:13]
	s_lshl_b64 s[6:7], s[4:5], 4
	s_mov_b64 s[8:9], 0
	v_mov_b32_e32 v192, v4
	s_mul_i32 s5, s4, 7
.Lxn8_head:
	v_add_u32_e32 v11, s5, v192
	v_cmp_gt_i32_e32 vcc, 0xc00000, v11
	s_andn2_b64 s[12:13], exec, vcc
	s_cbranch_scc1 .Lxn8_tail
	s_brev_b32 s12, 31
	s_mov_b32 s13, -1
	v_lshl_add_u64 v[8:9], v[192:193], 4, s[14:15]
	v_cmp_gt_i32_e32 vcc, s65, v192
	v_lshl_add_u64 v[8:9], v[8:9], 0, s[12:13]
	v_add_u32_e32 v192, s4, v192
	v_cndmask_b32_e32 v9, v9, v7, vcc
	v_cndmask_b32_e32 v8, v8, v6, vcc
	global_load_dwordx4 v[68:71], v[8:9], off
	v_lshl_add_u64 v[6:7], v[6:7], 0, s[6:7]
	v_lshl_add_u64 v[12:13], v[192:193], 4, s[14:15]
	v_cmp_gt_i32_e32 vcc, s65, v192
	v_lshl_add_u64 v[12:13], v[12:13], 0, s[12:13]
	v_add_u32_e32 v192, s4, v192
	v_cndmask_b32_e32 v13, v13, v7, vcc
	v_cndmask_b32_e32 v12, v12, v6, vcc
	global_load_dwordx4 v[72:75], v[12:13], off
	v_lshl_add_u64 v[6:7], v[6:7], 0, s[6:7]
	v_lshl_add_u64 v[14:15], v[192:193], 4, s[14:15]
	v_cmp_gt_i32_e32 vcc, s65, v192
	v_lshl_add_u64 v[14:15], v[14:15], 0, s[12:13]
	v_add_u32_e32 v192, s4, v192
	v_cndmask_b32_e32 v15, v15, v7, vcc
	v_cndmask_b32_e32 v14, v14, v6, vcc
	global_load_dwordx4 v[76:79], v[14:15], off
	v_lshl_add_u64 v[6:7], v[6:7], 0, s[6:7]
	v_lshl_add_u64 v[8:9], v[192:193], 4, s[14:15]
	v_cmp_gt_i32_e32 vcc, s65, v192
	v_lshl_add_u64 v[8:9], v[8:9], 0, s[12:13]
	v_add_u32_e32 v192, s4, v192
	v_cndmask_b32_e32 v9, v9, v7, vcc
	v_cndmask_b32_e32 v8, v8, v6, vcc
	global_load_dwordx4 v[80:83], v[8:9], off
	v_lshl_add_u64 v[6:7], v[6:7], 0, s[6:7]
	v_lshl_add_u64 v[12:13], v[192:193], 4, s[14:15]
	v_cmp_gt_i32_e32 vcc, s65, v192
	v_lshl_add_u64 v[12:13], v[12:13], 0, s[12:13]
	v_add_u32_e32 v192, s4, v192
	v_cndmask_b32_e32 v13, v13, v7, vcc
	v_cndmask_b32_e32 v12, v12, v6, vcc
	global_load_dwordx4 v[84:87], v[12:13], off
	v_lshl_add_u64 v[6:7], v[6:7], 0, s[6:7]
	v_lshl_add_u64 v[14:15], v[192:193], 4, s[14:15]
	v_cmp_gt_i32_e32 vcc, s65, v192
	v_lshl_add_u64 v[14:15], v[14:15], 0, s[12:13]
	v_add_u32_e32 v192, s4, v192
	v_cndmask_b32_e32 v15, v15, v7, vcc
	v_cndmask_b32_e32 v14, v14, v6, vcc
	global_load_dwordx4 v[88:91], v[14:15], off
	v_lshl_add_u64 v[6:7], v[6:7], 0, s[6:7]
	v_lshl_add_u64 v[8:9], v[192:193], 4, s[14:15]
	v_cmp_gt_i32_e32 vcc, s65, v192
	v_lshl_add_u64 v[8:9], v[8:9], 0, s[12:13]
	v_add_u32_e32 v192, s4, v192
	v_cndmask_b32_e32 v9, v9, v7, vcc
	v_cndmask_b32_e32 v8, v8, v6, vcc
	global_load_dwordx4 v[92:95], v[8:9], off
	v_lshl_add_u64 v[6:7], v[6:7], 0, s[6:7]
	v_lshl_add_u64 v[12:13], v[192:193], 4, s[14:15]
	v_cmp_gt_i32_e32 vcc, s65, v192
	v_lshl_add_u64 v[12:13], v[12:13], 0, s[12:13]
	v_add_u32_e32 v192, s4, v192
	v_cndmask_b32_e32 v13, v13, v7, vcc
	v_cndmask_b32_e32 v12, v12, v6, vcc
	global_load_dwordx4 v[96:99], v[12:13], off
	v_lshl_add_u64 v[6:7], v[6:7], 0, s[6:7]
	s_waitcnt vmcnt(0)
	v_cvt_pk_bf16_f32 v68, v68, v69
	v_cvt_pk_bf16_f32 v69, v70, v71
	global_store_dwordx2 v[2:3], v[68:69], off
	v_lshl_add_u64 v[2:3], v[2:3], 0, s[2:3]
	v_cvt_pk_bf16_f32 v72, v72, v73
	v_cvt_pk_bf16_f32 v73, v74, v75
	global_store_dwordx2 v[2:3], v[72:73], off
	v_lshl_add_u64 v[2:3], v[2:3], 0, s[2:3]
	v_cvt_pk_bf16_f32 v76, v76, v77
	v_cvt_pk_bf16_f32 v77, v78, v79
	global_store_dwordx2 v[2:3], v[76:77], off
	v_lshl_add_u64 v[2:3], v[2:3], 0, s[2:3]
	v_cvt_pk_bf16_f32 v80, v80, v81
	v_cvt_pk_bf16_f32 v81, v82, v83
	global_store_dwordx2 v[2:3], v[80:81], off
	v_lshl_add_u64 v[2:3], v[2:3], 0, s[2:3]
	v_cvt_pk_bf16_f32 v84, v84, v85
	v_cvt_pk_bf16_f32 v85, v86, v87
	global_store_dwordx2 v[2:3], v[84:85], off
	v_lshl_add_u64 v[2:3], v[2:3], 0, s[2:3]
	v_cvt_pk_bf16_f32 v88, v88, v89
	v_cvt_pk_bf16_f32 v89, v90, v91
	global_store_dwordx2 v[2:3], v[88:89], off
	v_lshl_add_u64 v[2:3], v[2:3], 0, s[2:3]
	v_cvt_pk_bf16_f32 v92, v92, v93
	v_cvt_pk_bf16_f32 v93, v94, v95
	global_store_dwordx2 v[2:3], v[92:93], off
	v_lshl_add_u64 v[2:3], v[2:3], 0, s[2:3]
	v_cvt_pk_bf16_f32 v96, v96, v97
	v_cvt_pk_bf16_f32 v97, v98, v99
	global_store_dwordx2 v[2:3], v[96:97], off
	v_lshl_add_u64 v[2:3], v[2:3], 0, s[2:3]
	s_branch .Lxn8_head
.Lxn8_tail:
	v_cmp_gt_i32_e32 vcc, 0xc00000, v192
	s_and_b64 exec, exec, vcc
	s_cbranch_execz .LBB0_757
